# same as the best combined version, with the out-phase unit remap guarded by gridDim.x == 256 (original dealing otherwise)
# speedup vs baseline: 1.0024x; 1.0008x over previous
; __global__ void __launch_bounds__(NT) mega(P p) {
;     ...
;     for (int u = blockIdx.x; u < 3 * NUNIT + (NUNIT - SB_M1); u += gridDim.x) {
;       if (u >= 3 * NUNIT) { sb_unit(p, SB_M1 + (u - 3 * NUNIT), smem); continue; }
;       const int kind = u / NUNIT, uu = u % NUNIT;
;       if (kind == 0) out_unit<0>(p, layer, uu, smem);
;       else if (kind == 1) out_unit<1>(p, layer, uu, smem);
;       else out_unit<2>(p, layer, uu, smem);
;     }
.LBB0_481:
	s_or_b64 exec, exec, s[0:1]
	v_readlane_b32 s0, v254, 44
	v_readlane_b32 s1, v254, 45
	s_andn2_b64 vcc, exec, s[0:1]
	s_waitcnt lgkmcnt(0)
	s_barrier
	s_cbranch_vccnz .LBB0_673
	v_readlane_b32 s0, v254, 61
	s_lshl_b32 s96, s0, 8
	v_readlane_b32 s12, v254, 25
	s_lshl_b64 s[0:1], s[96:97], 2
	v_readlane_b32 s24, v254, 37
	v_readlane_b32 s25, v254, 38
	s_add_u32 s60, s24, s0
	v_readlane_b32 s22, v254, 35
	s_addc_u32 s62, s25, s1
	v_readlane_b32 s23, v254, 36
	s_add_u32 s63, s22, s0
	v_readlane_b32 s14, v254, 27
	s_addc_u32 s64, s23, s1
	v_readlane_b32 s15, v254, 28
	s_add_u32 s65, s14, s0
	s_addc_u32 s66, s15, s1
	s_nop 0
	s_mov_b32 s33, s53
	s_mov_b32 s67, s78
	s_movk_i32 s69, 0x637
	s_mov_b32 s32, 0x7fffffff
	s_cmpk_lg_u32 s78, 0x100
	s_cbranch_scc1 .Lom3_done
	s_mul_i32 s33, s53, 7
	s_add_i32 s68, s53, 0x538
	s_cmpk_lt_i32 s33, 0x618
	s_cselect_b32 s33, s33, s68
	s_mov_b32 s67, 1
	s_movk_i32 s69, 0x617
	s_movk_i32 s32, 7

; template <int MX>
; __device__ void out_unit(const P& p, int layer, int unit, char* smem) {
;     ...
;       *(uint2*)(yp + 16 * et) = ov2;
; __global__ void __launch_bounds__(NT) mega(P p) {
;     ...
;     for (int u = blockIdx.x; u < 3 * NUNIT + (NUNIT - SB_M1); u += gridDim.x) {
;       if (u >= 3 * NUNIT) { sb_unit(p, SB_M1 + (u - 3 * NUNIT), smem); continue; }
;       const int kind = u / NUNIT, uu = u % NUNIT;
;       if (kind == 0) out_unit<0>(p, layer, uu, smem);
;       else if (kind == 1) out_unit<1>(p, layer, uu, smem);
;       else out_unit<2>(p, layer, uu, smem);
;     }
.LBB0_484:
	s_add_i32 s33, s33, s67
	s_add_i32 s58, s58, 1
	s_add_i32 s68, s33, 0xfffffbd0
	s_cmp_gt_i32 s33, s69
	s_cselect_b32 s57, s32, s58
	s_cmp_ge_i32 s57, s32
	v_mov_b32_e32 v208, v30
	global_store_dwordx2 v[4:5], v[0:1], off offset:96
	s_cbranch_scc1 .LBB0_672
